# sample-MLA: the wave without a score duty issues its key-tile LDS-DMA block after its value MFMAs instead of at step start
# speedup vs baseline: 1.0019x; 1.0019x over previous
.LBB0_1120:
	s_cmp_lg_u64 s[66:67], 0
	s_cbranch_scc0 .LBB0_1144

.Lpv_prio_done:
	ds_read_b64_tr_b16 v[204:205], v200 offset:1536
	ds_read_b64_tr_b16 v[206:207], v200 offset:9728
	s_waitcnt lgkmcnt(6)
	v_mfma_f32_32x32x16_bf16 v[6:21], v[138:141], v[142:145], v[6:21]
	ds_read_b64_tr_b16 v[142:143], v200 offset:2048
	ds_read_b64_tr_b16 v[144:145], v200 offset:10240
	s_waitcnt lgkmcnt(6)
	v_mfma_f32_32x32x16_bf16 v[118:133], v[138:141], v[146:149], v[118:133]
	ds_read_b64_tr_b16 v[146:147], v200 offset:2560
	ds_read_b64_tr_b16 v[148:149], v200 offset:10752
	s_waitcnt lgkmcnt(6)
	v_mfma_f32_32x32x16_bf16 v[102:117], v[138:141], v[248:251], v[102:117]
	ds_read_b64_tr_b16 v[248:249], v200 offset:3072
	ds_read_b64_tr_b16 v[250:251], v200 offset:11264
	s_waitcnt lgkmcnt(6)
	v_mfma_f32_32x32x16_bf16 v[86:101], v[138:141], v[204:207], v[86:101]
	ds_read_b64_tr_b16 v[204:205], v200 offset:3584
	ds_read_b64_tr_b16 v[206:207], v200 offset:11776
	s_waitcnt lgkmcnt(6)
	v_mfma_f32_32x32x16_bf16 v[70:85], v[138:141], v[142:145], v[70:85]
	ds_read_b64_tr_b16 v[142:143], v1 offset:0
	ds_read_b64_tr_b16 v[144:145], v1 offset:8192
	s_waitcnt lgkmcnt(6)
	v_mfma_f32_32x32x16_bf16 v[54:69], v[138:141], v[146:149], v[54:69]
	ds_read_b64_tr_b16 v[146:147], v1 offset:512
	ds_read_b64_tr_b16 v[148:149], v1 offset:8704
	s_waitcnt lgkmcnt(6)
	v_mfma_f32_32x32x16_bf16 v[38:53], v[138:141], v[248:251], v[38:53]
	ds_read_b64_tr_b16 v[248:249], v1 offset:1024
	ds_read_b64_tr_b16 v[250:251], v1 offset:9216
	s_waitcnt lgkmcnt(6)
	v_mfma_f32_32x32x16_bf16 v[22:37], v[138:141], v[204:207], v[22:37]
	ds_read_b64_tr_b16 v[204:205], v1 offset:1536
	ds_read_b64_tr_b16 v[206:207], v1 offset:9728
	s_waitcnt lgkmcnt(6)
	v_mfma_f32_32x32x16_bf16 v[6:21], v[134:137], v[142:145], v[6:21]
	ds_read_b64_tr_b16 v[142:143], v1 offset:2048
	ds_read_b64_tr_b16 v[144:145], v1 offset:10240
	s_waitcnt lgkmcnt(6)
	v_mfma_f32_32x32x16_bf16 v[118:133], v[134:137], v[146:149], v[118:133]
	ds_read_b64_tr_b16 v[146:147], v1 offset:2560
	ds_read_b64_tr_b16 v[148:149], v1 offset:10752
	s_waitcnt lgkmcnt(6)
	v_mfma_f32_32x32x16_bf16 v[102:117], v[134:137], v[248:251], v[102:117]
	ds_read_b64_tr_b16 v[248:249], v1 offset:3072
	ds_read_b64_tr_b16 v[250:251], v1 offset:11264
	s_waitcnt lgkmcnt(6)
	v_mfma_f32_32x32x16_bf16 v[86:101], v[134:137], v[204:207], v[86:101]
	ds_read_b64_tr_b16 v[204:205], v1 offset:3584
	ds_read_b64_tr_b16 v[206:207], v1 offset:11776
	s_waitcnt lgkmcnt(6)
	v_mfma_f32_32x32x16_bf16 v[70:85], v[134:137], v[142:145], v[70:85]
	s_waitcnt lgkmcnt(4)
	v_mfma_f32_32x32x16_bf16 v[54:69], v[134:137], v[146:149], v[54:69]
	s_waitcnt lgkmcnt(2)
	v_mfma_f32_32x32x16_bf16 v[38:53], v[134:137], v[248:251], v[38:53]
	s_waitcnt lgkmcnt(0)
	v_mfma_f32_32x32x16_bf16 v[22:37], v[134:137], v[204:207], v[22:37]
	s_setprio 0
	s_andn2_b64 vcc, exec, s[66:67]
	s_cbranch_vccnz .Lk2_entry
	s_mul_hi_u32 s19, s1, 0xaaaaaaab
	s_lshr_b32 s19, s19, 2
	s_mul_i32 s19, s19, 0xffff0d00
	s_add_i32 s19, s19, 0
	s_add_i32 s19, s19, s81
	v_add_u32_e32 v1, s19, v242
	v_add_u32_e32 v200, s14, v1
	v_add3_u32 v134, v200, v231, v232
	v_add3_u32 v138, v200, v230, v232
	ds_read_b128 v[134:137], v134
	ds_read_b128 v[204:207], v138
	v_add3_u32 v208, v200, v228, v232
	ds_read_b128 v[248:251], v208
	s_setprio 1
	s_waitcnt lgkmcnt(2)
	v_mfma_f32_32x32x16_bf16 v[134:149], v[134:137], v[194:197], 0
	s_waitcnt lgkmcnt(1)
	v_mfma_f32_32x32x16_bf16 v[134:149], v[204:207], v[190:193], v[134:149]
	v_add3_u32 v208, v200, v227, v232
	ds_read_b128 v[204:207], v208
	s_waitcnt lgkmcnt(1)
	v_mfma_f32_32x32x16_bf16 v[134:149], v[248:251], v[186:189], v[134:149]
	v_add3_u32 v208, v200, v236, v232
	ds_read_b128 v[248:251], v208
	s_waitcnt lgkmcnt(1)
	v_mfma_f32_32x32x16_bf16 v[134:149], v[204:207], v[182:185], v[134:149]
	v_add3_u32 v208, v200, v235, v232
	ds_read_b128 v[204:207], v208
	s_waitcnt lgkmcnt(1)
	v_mfma_f32_32x32x16_bf16 v[134:149], v[248:251], v[178:181], v[134:149]
	v_add3_u32 v208, v200, v234, v232
	ds_read_b128 v[248:251], v208
	s_waitcnt lgkmcnt(1)
	v_mfma_f32_32x32x16_bf16 v[134:149], v[204:207], v[174:177], v[134:149]
	v_add3_u32 v208, v200, v233, v232
	ds_read_b128 v[204:207], v208
	s_waitcnt lgkmcnt(1)
	v_mfma_f32_32x32x16_bf16 v[134:149], v[248:251], v[170:173], v[134:149]
	v_add3_u32 v208, v1, v231, v226
	ds_read_b128 v[248:251], v208 offset:8192
	s_waitcnt lgkmcnt(1)
	v_mfma_f32_32x32x16_bf16 v[134:149], v[204:207], v[166:169], v[134:149]
	v_add3_u32 v208, v1, v230, v226
	ds_read_b128 v[204:207], v208 offset:8192
	s_waitcnt lgkmcnt(1)
	v_mfma_f32_32x32x16_bf16 v[134:149], v[248:251], v[162:165], v[134:149]
	v_add3_u32 v208, v1, v228, v226
	ds_read_b128 v[248:251], v208 offset:8192
	s_waitcnt lgkmcnt(1)
	v_mfma_f32_32x32x16_bf16 v[134:149], v[204:207], v[158:161], v[134:149]
	v_add3_u32 v208, v1, v227, v226
	ds_read_b128 v[204:207], v208 offset:8192
	s_waitcnt lgkmcnt(1)
	v_mfma_f32_32x32x16_bf16 v[134:149], v[248:251], v[154:157], v[134:149]
	s_waitcnt lgkmcnt(0)
	v_mfma_f32_32x32x16_bf16 v[134:149], v[204:207], v[150:153], v[134:149]
	s_setprio 0
	v_add_u32_e32 v1, s15, v198
	v_add_u32_e32 v208, s19, v1
	v_add_u32_e32 v1, 0x1b900, v208
	ds_read_b128 v[204:207], v1
	v_add_u32_e32 v1, 0x1b920, v208
	ds_read_b128 v[248:251], v1
	s_waitcnt lgkmcnt(1)
	s_nop 5
	v_fma_f32 v1, v134, v204, -v213
	v_fma_f32 v134, v135, v205, -v213
	v_exp_f32_e32 v1, v1
	v_fma_f32 v135, v136, v206, -v213
	v_exp_f32_e32 v200, v134
	v_fma_f32 v136, v137, v207, -v213
	v_exp_f32_e32 v204, v135
	v_exp_f32_e32 v205, v136
	s_waitcnt lgkmcnt(0)
	v_fma_f32 v135, v138, v248, -v213
	v_add_f32_e32 v134, 0, v1
	v_exp_f32_e32 v206, v135
	v_add_f32_e32 v134, v200, v134
	v_add_f32_e32 v134, v204, v134
	v_add_f32_e32 v134, v205, v134
	v_add_f32_e32 v138, v206, v134
	v_fma_f32 v134, v139, v249, -v213
	v_exp_f32_e32 v207, v134
	v_fma_f32 v134, v140, v250, -v213
	v_exp_f32_e32 v248, v134
	v_fma_f32 v134, v141, v251, -v213
	v_exp_f32_e32 v249, v134
	v_add_u32_e32 v139, 0x1e180, v208
	v_add_f32_e32 v138, v207, v138
	ds_read_b128 v[134:137], v139
	v_add_f32_e32 v138, v248, v138
	v_add_f32_e32 v208, v249, v138
	ds_read_b128 v[138:141], v139 offset:32
	s_waitcnt lgkmcnt(1)
	v_fma_f32 v134, v142, v134, -v213
	v_exp_f32_e32 v134, v134
	v_fma_f32 v135, v143, v135, -v213
	s_waitcnt lgkmcnt(0)
	v_fma_f32 v138, v146, v138, -v213
	v_exp_f32_e32 v135, v135
	v_fma_f32 v136, v144, v136, -v213
	v_exp_f32_e32 v143, v138
	v_fma_f32 v138, v147, v139, -v213
	v_exp_f32_e32 v136, v136
	v_fma_f32 v137, v145, v137, -v213
	v_exp_f32_e32 v144, v138
	v_fma_f32 v138, v148, v140, -v213
	v_exp_f32_e32 v137, v137
	v_exp_f32_e32 v145, v138
	v_fma_f32 v138, v149, v141, -v213
	v_add_f32_e32 v142, v134, v208
	v_exp_f32_e32 v146, v138
	v_add_f32_e32 v142, v135, v142
	v_add_f32_e32 v142, v136, v142
	v_add_f32_e32 v142, v137, v142
	v_cvt_pk_bf16_f32 v138, v1, v200
	v_cvt_pk_bf16_f32 v139, v204, v205
	v_cvt_pk_bf16_f32 v140, v206, v207
	v_cvt_pk_bf16_f32 v141, v248, v249
	s_nop 0
	v_permlane32_swap_b32_e32 v138, v140
	v_permlane32_swap_b32_e32 v139, v141
	v_cvt_pk_bf16_f32 v134, v134, v135
	v_cvt_pk_bf16_f32 v135, v136, v137
	v_cvt_pk_bf16_f32 v136, v143, v144
	v_cvt_pk_bf16_f32 v137, v145, v146
	v_add_f32_e32 v1, v143, v142
	v_permlane32_swap_b32_e32 v134, v136
	v_permlane32_swap_b32_e32 v135, v137
	v_add_f32_e32 v1, v144, v1
	ds_write_b128 v223, v[138:141]
	ds_write_b128 v223, v[134:137] offset:16
	v_add_f32_e32 v1, v145, v1
	s_waitcnt lgkmcnt(0)
	v_add_f32_e32 v1, v146, v1
	v_add_f32_e32 v2, v2, v1
	s_branch .LBB0_1105
	s_nop 0
	s_nop 0
	s_nop 0
	s_nop 0
	s_nop 0
	s_nop 0
	s_nop 0
	s_nop 0
	s_nop 0
	s_nop 0
	s_nop 0
	s_nop 0
	s_nop 0
	s_nop 0
	s_nop 0
	s_nop 0
	s_nop 0
	s_nop 0
	s_nop 0
	s_nop 0
	s_nop 0
	s_nop 0
